# gdn_fix loop: data load issued with the ssq load (one wait per iteration instead of two)
# speedup vs baseline: 1.0045x; 1.0045x over previous
; DI unsigned pack2(float lo, float hi) { f32x2 v = {lo, hi}; bf2_t b = __builtin_convertvector(v, bf2_t); return __builtin_bit_cast(unsigned, b); }
; DI void unpack8(const u32x4& v, float* f) { f[0] = bflo(v.x); f[1] = bfhi(v.x); f[2] = bflo(v.y); f[3] = bfhi(v.y); f[4] = bflo(v.z); f[5] = bfhi(v.z); f[6] = bflo(v.w); f[7] = bfhi(v.w); }
; DI float row16_sum(float v) { v += dppf<0xB1>(v); v += dppf<0x4E>(v); v += dppf<0x141>(v); v += dppf<0x140>(v); return v; }
; DI void gdn_fix_phase(const Params& P) {
;     ...
;   for (int idx = blockIdx.x * NT + tid; idx < S_ * 128; idx += gridDim.x * NT) {
;     const int t = idx >> 7, ck = idx & 127, h = ck >> 4;
;     const int p = (tid & 15) >> 1;
;     float sq = ((tid & 1) == 0) ? ssqp[((size_t)p * S_ + t) * 8 + h] : 0.f;
;     sq = row16_sum(sq);
;     const float r = rsqrtf(sq * (1.f / 128.f) + EPS);
;     u32x4* pp = (u32x4*)(mixin + (size_t)t * 2048 + ck * 8); const u32x4 v = *pp; float f[8]; unpack8(v, f);
;     u32x4 o = {pack2(f[0] * r, f[1] * r), pack2(f[2] * r, f[3] * r), pack2(f[4] * r, f[5] * r), pack2(f[6] * r, f[7] * r)}; *pp = o;
;   }
.LBB0_755:
	s_or_b64 exec, exec, s[2:3]
	s_waitcnt vmcnt(0) lgkmcnt(0)
	v_add_f32_dpp v9, v9, v9 quad_perm:[1,0,3,2] row_mask:0xf bank_mask:0xf bound_ctrl:1
	v_lshlrev_b64 v[6:7], 12, v[6:7]
	v_lshl_add_u64 v[6:7], v[4:5], 0, v[6:7]
	v_add_f32_dpp v9, v9, v9 quad_perm:[2,3,0,1] row_mask:0xf bank_mask:0xf bound_ctrl:1
	s_nop 1
	v_add_f32_dpp v9, v9, v9 row_half_mirror row_mask:0xf bank_mask:0xf bound_ctrl:1
	s_nop 1
	v_add_f32_dpp v9, v9, v9 row_mirror row_mask:0xf bank_mask:0xf bound_ctrl:1
	v_fmamk_f32 v9, v9, 0x3c000000, v245
	v_cmp_gt_f32_e64 s[2:3], s84, v9
	v_mul_f32_e32 v10, 0x4b800000, v9
	s_nop 0
	v_cndmask_b32_e64 v9, v9, v10, s[2:3]
	v_rsq_f32_e32 v9, v9
	s_nop 0
	v_mul_f32_e32 v10, 0x45800000, v9
	v_cndmask_b32_e64 v14, v9, v10, s[2:3]
	v_readlane_b32 s2, v254, 60
	v_lshlrev_b32_e32 v16, 16, v22
	v_and_b32_e32 v17, 0xffff0000, v22
	v_pk_mul_f32 v[16:17], v[14:15], v[16:17] op_sel_hi:[0,1]
	v_cvt_pk_bf16_f32 v10, v16, v17
	v_lshlrev_b32_e32 v16, 16, v23
	v_and_b32_e32 v17, 0xffff0000, v23
	v_pk_mul_f32 v[16:17], v[14:15], v[16:17] op_sel_hi:[0,1]
	v_cvt_pk_bf16_f32 v11, v16, v17
	v_lshlrev_b32_e32 v16, 16, v24
	v_and_b32_e32 v17, 0xffff0000, v24
	v_pk_mul_f32 v[16:17], v[14:15], v[16:17] op_sel_hi:[0,1]
	v_cvt_pk_bf16_f32 v12, v16, v17
	v_lshlrev_b32_e32 v16, 16, v25
	v_and_b32_e32 v17, 0xffff0000, v25
	v_add_u32_e32 v8, s2, v8
	s_mov_b32 s2, 0x1fffff
	v_pk_mul_f32 v[14:15], v[14:15], v[16:17] op_sel_hi:[0,1]
	v_cmp_lt_i32_e64 s[2:3], s2, v8
	v_cvt_pk_bf16_f32 v13, v14, v15
	s_or_b64 s[4:5], s[2:3], s[4:5]
	global_store_dwordx4 v[6:7], v[10:13], off
	s_andn2_b64 exec, exec, s[4:5]
	s_cbranch_execz .LBB0_758
.LBB0_756:
	v_ashrrev_i32_e32 v6, 7, v8
	v_ashrrev_i32_e32 v7, 31, v6
	v_lshlrev_b64 v[18:19], 12, v[6:7]
	v_lshl_add_u64 v[18:19], v[4:5], 0, v[18:19]
	global_load_dwordx4 v[22:25], v[18:19], off
	v_mov_b32_e32 v9, 0
	s_and_saveexec_b64 s[2:3], vcc
	s_cbranch_execz .LBB0_755
	v_lshl_add_u64 v[20:21], v[6:7], 0, v[0:1]
	v_lshlrev_b64 v[20:21], 5, v[20:21]
	v_lshl_add_u64 v[20:21], v[2:3], 0, v[20:21]
	global_load_dword v9, v[20:21], off
	s_branch .LBB0_755
